# mem-attention unit: key-image staging issues its 16 loads before the LDS writes (was 4 trips of load-4, wait, write)
# baseline (speedup 1.0000x reference)
.LBB0_660:
	v_lshl_add_u64 v[212:213], v[10:11], 0, v[2:3]
	global_load_dwordx4 v[38:41], v[212:213], off
	v_lshl_add_u64 v[212:213], v[4:5], 0, v[2:3]
	global_load_dwordx4 v[42:45], v[212:213], off
	v_lshl_add_u64 v[212:213], v[8:9], 0, v[2:3]
	global_load_dwordx4 v[46:49], v[212:213], off
	v_lshl_add_u64 v[212:213], v[6:7], 0, v[2:3]
	global_load_dwordx4 v[50:53], v[212:213], off
	v_lshl_add_u64 v[10:11], v[10:11], 0, s[12:13]
	v_lshl_add_u64 v[4:5], v[4:5], 0, s[12:13]
	v_lshl_add_u64 v[8:9], v[8:9], 0, s[12:13]
	v_lshl_add_u64 v[6:7], v[6:7], 0, s[12:13]
	v_lshl_add_u64 v[212:213], v[10:11], 0, v[2:3]
	global_load_dwordx4 v[54:57], v[212:213], off
	v_lshl_add_u64 v[212:213], v[4:5], 0, v[2:3]
	global_load_dwordx4 v[58:61], v[212:213], off
	v_lshl_add_u64 v[212:213], v[8:9], 0, v[2:3]
	global_load_dwordx4 v[62:65], v[212:213], off
	v_lshl_add_u64 v[212:213], v[6:7], 0, v[2:3]
	global_load_dwordx4 v[66:69], v[212:213], off
	v_lshl_add_u64 v[10:11], v[10:11], 0, s[12:13]
	v_lshl_add_u64 v[4:5], v[4:5], 0, s[12:13]
	v_lshl_add_u64 v[8:9], v[8:9], 0, s[12:13]
	v_lshl_add_u64 v[6:7], v[6:7], 0, s[12:13]
	v_lshl_add_u64 v[212:213], v[10:11], 0, v[2:3]
	global_load_dwordx4 v[70:73], v[212:213], off
	v_lshl_add_u64 v[212:213], v[4:5], 0, v[2:3]
	global_load_dwordx4 v[74:77], v[212:213], off
	v_lshl_add_u64 v[212:213], v[8:9], 0, v[2:3]
	global_load_dwordx4 v[78:81], v[212:213], off
	v_lshl_add_u64 v[212:213], v[6:7], 0, v[2:3]
	global_load_dwordx4 v[82:85], v[212:213], off
	v_lshl_add_u64 v[10:11], v[10:11], 0, s[12:13]
	v_lshl_add_u64 v[4:5], v[4:5], 0, s[12:13]
	v_lshl_add_u64 v[8:9], v[8:9], 0, s[12:13]
	v_lshl_add_u64 v[6:7], v[6:7], 0, s[12:13]
	v_lshl_add_u64 v[212:213], v[10:11], 0, v[2:3]
	global_load_dwordx4 v[86:89], v[212:213], off
	v_lshl_add_u64 v[212:213], v[4:5], 0, v[2:3]
	global_load_dwordx4 v[200:203], v[212:213], off
	v_lshl_add_u64 v[212:213], v[8:9], 0, v[2:3]
	global_load_dwordx4 v[204:207], v[212:213], off
	v_lshl_add_u64 v[212:213], v[6:7], 0, v[2:3]
	global_load_dwordx4 v[208:211], v[212:213], off
	v_add_u32_e32 v214, v15, v90
	s_waitcnt vmcnt(15)
	ds_write_b128 v214, v[38:41]
	v_add_u32_e32 v214, v16, v90
	s_waitcnt vmcnt(14)
	ds_write_b128 v214, v[42:45]
	v_add_u32_e32 v214, v14, v90
	s_waitcnt vmcnt(13)
	ds_write_b128 v214, v[46:49]
	v_add_u32_e32 v214, v13, v90
	s_waitcnt vmcnt(12)
	ds_write_b128 v214, v[50:53]
	v_add_u32_e32 v15, 0x8400, v15
	v_add_u32_e32 v16, 0x8400, v16
	v_add_u32_e32 v14, 0x8400, v14
	v_add_u32_e32 v13, 0x8400, v13
	v_add_u32_e32 v214, v15, v90
	s_waitcnt vmcnt(11)
	ds_write_b128 v214, v[54:57]
	v_add_u32_e32 v214, v16, v90
	s_waitcnt vmcnt(10)
	ds_write_b128 v214, v[58:61]
	v_add_u32_e32 v214, v14, v90
	s_waitcnt vmcnt(9)
	ds_write_b128 v214, v[62:65]
	v_add_u32_e32 v214, v13, v90
	s_waitcnt vmcnt(8)
	ds_write_b128 v214, v[66:69]
	v_add_u32_e32 v15, 0x8400, v15
	v_add_u32_e32 v16, 0x8400, v16
	v_add_u32_e32 v14, 0x8400, v14
	v_add_u32_e32 v13, 0x8400, v13
	v_add_u32_e32 v214, v15, v90
	s_waitcnt vmcnt(7)
	ds_write_b128 v214, v[70:73]
	v_add_u32_e32 v214, v16, v90
	s_waitcnt vmcnt(6)
	ds_write_b128 v214, v[74:77]
	v_add_u32_e32 v214, v14, v90
	s_waitcnt vmcnt(5)
	ds_write_b128 v214, v[78:81]
	v_add_u32_e32 v214, v13, v90
	s_waitcnt vmcnt(4)
	ds_write_b128 v214, v[82:85]
	v_add_u32_e32 v15, 0x8400, v15
	v_add_u32_e32 v16, 0x8400, v16
	v_add_u32_e32 v14, 0x8400, v14
	v_add_u32_e32 v13, 0x8400, v13
	v_add_u32_e32 v214, v15, v90
	s_waitcnt vmcnt(3)
	ds_write_b128 v214, v[86:89]
	v_add_u32_e32 v214, v16, v90
	s_waitcnt vmcnt(2)
	ds_write_b128 v214, v[200:203]
	v_add_u32_e32 v214, v14, v90
	s_waitcnt vmcnt(1)
	ds_write_b128 v214, v[204:207]
	v_add_u32_e32 v214, v13, v90
	s_waitcnt vmcnt(0)
	ds_write_b128 v214, v[208:211]
	s_or_b64 exec, exec, s[20:21]
	s_lshl_b32 s20, s42, 7
	s_and_b32 s20, s20, 0xf80
	s_and_b32 s45, s23, 3
	s_add_i32 s44, s20, s28
	s_lshl_b32 s20, s22, 8
	s_lshl_b32 s43, s22, 12
	s_lshl_b32 s0, s0, 18
	s_ashr_i32 s21, s20, 31
	s_add_i32 s44, s44, s43
	s_lshl_b32 s46, s45, 9
	s_add_u32 s22, s29, s46
	s_addc_u32 s23, s30, 0
	v_or_b32_e32 v190, s44, v106
	v_mov_b64_e32 v[2:3], s[22:23]
	v_mad_i64_i32 v[2:3], s[22:23], v190, s39, v[2:3]
	v_mov_b32_e32 v103, v91
	v_lshl_add_u64 v[2:3], v[2:3], 0, v[102:103]
	global_load_dwordx4 v[58:61], v[2:3], off
	global_load_dwordx4 v[86:89], v[2:3], off offset:64
	global_load_dwordx4 v[82:85], v[2:3], off offset:128
	global_load_dwordx4 v[78:81], v[2:3], off offset:192
	global_load_dwordx4 v[74:77], v[2:3], off offset:256
	global_load_dwordx4 v[70:73], v[2:3], off offset:320
	global_load_dwordx4 v[62:65], v[2:3], off offset:384
	global_load_dwordx4 v[66:69], v[2:3], off offset:448
	s_waitcnt lgkmcnt(0)
	s_barrier
	ds_read_b128 v[2:5], v108
	ds_read_b128 v[6:9], v108 offset:64
	ds_read_b128 v[10:13], v108 offset:8448
	ds_read_b128 v[14:17], v108 offset:8512
	s_waitcnt vmcnt(7) lgkmcnt(3)
	v_mfma_f32_16x16x32_bf16 v[2:5], v[2:5], v[58:61], 0
	s_waitcnt lgkmcnt(1)
	v_mfma_f32_16x16x32_bf16 v[10:13], v[10:13], v[58:61], 0
	s_waitcnt vmcnt(6)
	v_mfma_f32_16x16x32_bf16 v[2:5], v[6:9], v[86:89], v[2:5]
	s_waitcnt lgkmcnt(0)
	v_mfma_f32_16x16x32_bf16 v[6:9], v[14:17], v[86:89], v[10:13]
	s_nop 3
	ds_read_b128 v[10:13], v108 offset:128
	ds_read_b128 v[14:17], v108 offset:192
	s_waitcnt vmcnt(5) lgkmcnt(1)
	v_mfma_f32_16x16x32_bf16 v[2:5], v[10:13], v[82:85], v[2:5]
	ds_read_b128 v[10:13], v108 offset:8576
	ds_read_b128 v[18:21], v108 offset:8640
	s_waitcnt lgkmcnt(1)
	v_mfma_f32_16x16x32_bf16 v[6:9], v[10:13], v[82:85], v[6:9]
	s_waitcnt vmcnt(4)
	v_mfma_f32_16x16x32_bf16 v[2:5], v[14:17], v[78:81], v[2:5]
	ds_read_b128 v[10:13], v108 offset:256
	ds_read_b128 v[14:17], v108 offset:320
	s_waitcnt lgkmcnt(2)
	v_mfma_f32_16x16x32_bf16 v[6:9], v[18:21], v[78:81], v[6:9]
	s_waitcnt vmcnt(3) lgkmcnt(1)
	v_mfma_f32_16x16x32_bf16 v[2:5], v[10:13], v[74:77], v[2:5]
	ds_read_b128 v[10:13], v108 offset:8704
	ds_read_b128 v[18:21], v108 offset:8768
	s_waitcnt lgkmcnt(1)
	v_mfma_f32_16x16x32_bf16 v[6:9], v[10:13], v[74:77], v[6:9]
	s_waitcnt vmcnt(2)
	v_mfma_f32_16x16x32_bf16 v[2:5], v[14:17], v[70:73], v[2:5]
	ds_read_b128 v[10:13], v108 offset:384
	ds_read_b128 v[14:17], v108 offset:448
	s_waitcnt lgkmcnt(2)
	v_mfma_f32_16x16x32_bf16 v[6:9], v[18:21], v[70:73], v[6:9]
	s_waitcnt vmcnt(1) lgkmcnt(1)
	v_mfma_f32_16x16x32_bf16 v[2:5], v[10:13], v[62:65], v[2:5]
	ds_read_b128 v[10:13], v108 offset:8832
	ds_read_b128 v[18:21], v108 offset:8896
	s_waitcnt lgkmcnt(1)
	v_mfma_f32_16x16x32_bf16 v[10:13], v[10:13], v[62:65], v[6:9]
	s_waitcnt vmcnt(0)
	v_mfma_f32_16x16x32_bf16 v[6:9], v[14:17], v[66:69], v[2:5]
	s_waitcnt lgkmcnt(0)
	v_mfma_f32_16x16x32_bf16 v[2:5], v[18:21], v[66:69], v[10:13]
	s_nop 3
	ds_read_b128 v[10:13], v108 offset:16896
	ds_read_b128 v[14:17], v108 offset:16960
	ds_read_b128 v[18:21], v108 offset:25344
	ds_read_b128 v[22:25], v108 offset:25408
	ds_read_b128 v[26:29], v108 offset:17024
	s_waitcnt lgkmcnt(4)
	v_mfma_f32_16x16x32_bf16 v[10:13], v[10:13], v[58:61], 0
	s_waitcnt lgkmcnt(3)
	v_mfma_f32_16x16x32_bf16 v[10:13], v[14:17], v[86:89], v[10:13]
	ds_read_b128 v[14:17], v108 offset:17088
	s_waitcnt lgkmcnt(1)
	v_mfma_f32_16x16x32_bf16 v[10:13], v[26:29], v[82:85], v[10:13]
	ds_read_b128 v[26:29], v108 offset:17152
	v_mfma_f32_16x16x32_bf16 v[18:21], v[18:21], v[58:61], 0
	s_waitcnt lgkmcnt(1)
	v_mfma_f32_16x16x32_bf16 v[10:13], v[14:17], v[78:81], v[10:13]
	ds_read_b128 v[14:17], v108 offset:17216
	s_waitcnt lgkmcnt(1)
	v_mfma_f32_16x16x32_bf16 v[10:13], v[26:29], v[74:77], v[10:13]
	ds_read_b128 v[26:29], v108 offset:17280
	s_waitcnt lgkmcnt(1)
	v_mfma_f32_16x16x32_bf16 v[10:13], v[14:17], v[70:73], v[10:13]
	ds_read_b128 v[14:17], v108 offset:17344
	s_waitcnt lgkmcnt(1)
	v_mfma_f32_16x16x32_bf16 v[10:13], v[26:29], v[62:65], v[10:13]
	s_waitcnt lgkmcnt(0)
	v_mfma_f32_16x16x32_bf16 v[10:13], v[14:17], v[66:69], v[10:13]
	ds_read_b128 v[14:17], v108 offset:25472
	v_mfma_f32_16x16x32_bf16 v[18:21], v[22:25], v[86:89], v[18:21]
	ds_read_b128 v[22:25], v108 offset:25536
	s_waitcnt lgkmcnt(1)
	v_mfma_f32_16x16x32_bf16 v[14:17], v[14:17], v[82:85], v[18:21]
	s_nop 4
	ds_read_b128 v[18:21], v108 offset:25600
	s_waitcnt lgkmcnt(1)
	v_mfma_f32_16x16x32_bf16 v[14:17], v[22:25], v[78:81], v[14:17]
	ds_read_b128 v[22:25], v108 offset:25664
	s_waitcnt lgkmcnt(1)
	v_mfma_f32_16x16x32_bf16 v[14:17], v[18:21], v[74:77], v[14:17]
	ds_read_b128 v[18:21], v108 offset:25728
	s_waitcnt lgkmcnt(1)
	v_mfma_f32_16x16x32_bf16 v[14:17], v[22:25], v[70:73], v[14:17]
	ds_read_b128 v[22:25], v108 offset:25792
	s_waitcnt lgkmcnt(1)
	v_mfma_f32_16x16x32_bf16 v[14:17], v[18:21], v[62:65], v[14:17]
	s_waitcnt lgkmcnt(0)
	v_mfma_f32_16x16x32_bf16 v[14:17], v[22:25], v[66:69], v[14:17]
	ds_read_b128 v[18:21], v108 offset:33792
	ds_read_b128 v[22:25], v108 offset:33856
	ds_read_b128 v[26:29], v108 offset:42240
	ds_read_b128 v[30:33], v108 offset:42304
	ds_read_b128 v[34:37], v108 offset:33920
	s_waitcnt lgkmcnt(4)
	v_mfma_f32_16x16x32_bf16 v[18:21], v[18:21], v[58:61], 0
	s_waitcnt lgkmcnt(3)
	v_mfma_f32_16x16x32_bf16 v[18:21], v[22:25], v[86:89], v[18:21]
	ds_read_b128 v[22:25], v108 offset:33984
	s_waitcnt lgkmcnt(1)
	v_mfma_f32_16x16x32_bf16 v[18:21], v[34:37], v[82:85], v[18:21]
	ds_read_b128 v[34:37], v108 offset:34048
	v_mfma_f32_16x16x32_bf16 v[26:29], v[26:29], v[58:61], 0
	s_waitcnt lgkmcnt(1)
	v_mfma_f32_16x16x32_bf16 v[18:21], v[22:25], v[78:81], v[18:21]
	ds_read_b128 v[22:25], v108 offset:34112
	s_waitcnt lgkmcnt(1)
	v_mfma_f32_16x16x32_bf16 v[18:21], v[34:37], v[74:77], v[18:21]
	ds_read_b128 v[34:37], v108 offset:34176
	s_waitcnt lgkmcnt(1)
	v_mfma_f32_16x16x32_bf16 v[18:21], v[22:25], v[70:73], v[18:21]
	ds_read_b128 v[22:25], v108 offset:34240
	s_waitcnt lgkmcnt(1)
	v_mfma_f32_16x16x32_bf16 v[18:21], v[34:37], v[62:65], v[18:21]
	s_waitcnt lgkmcnt(0)
	v_mfma_f32_16x16x32_bf16 v[18:21], v[22:25], v[66:69], v[18:21]
	ds_read_b128 v[22:25], v108 offset:42368
	v_mfma_f32_16x16x32_bf16 v[26:29], v[30:33], v[86:89], v[26:29]
	ds_read_b128 v[30:33], v108 offset:42432
	s_waitcnt lgkmcnt(1)
	v_mfma_f32_16x16x32_bf16 v[22:25], v[22:25], v[82:85], v[26:29]
	s_nop 4
	ds_read_b128 v[26:29], v108 offset:42496
	s_waitcnt lgkmcnt(1)
	v_mfma_f32_16x16x32_bf16 v[22:25], v[30:33], v[78:81], v[22:25]
	ds_read_b128 v[30:33], v108 offset:42560
	s_waitcnt lgkmcnt(1)
	v_mfma_f32_16x16x32_bf16 v[22:25], v[26:29], v[74:77], v[22:25]
	ds_read_b128 v[26:29], v108 offset:42624
	s_waitcnt lgkmcnt(1)
	v_mfma_f32_16x16x32_bf16 v[22:25], v[30:33], v[70:73], v[22:25]
	ds_read_b128 v[30:33], v108 offset:42688
	s_waitcnt lgkmcnt(1)
	v_mfma_f32_16x16x32_bf16 v[22:25], v[26:29], v[62:65], v[22:25]
	s_waitcnt lgkmcnt(0)
	v_mfma_f32_16x16x32_bf16 v[22:25], v[30:33], v[66:69], v[22:25]
	ds_read_b128 v[26:29], v108 offset:50688
	ds_read_b128 v[30:33], v108 offset:50752
	ds_read_b128 v[34:37], v108 offset:59136
	ds_read_b128 v[38:41], v108 offset:59200
	ds_read_b128 v[42:45], v108 offset:50816
	s_waitcnt lgkmcnt(4)
	v_mfma_f32_16x16x32_bf16 v[26:29], v[26:29], v[58:61], 0
	s_waitcnt lgkmcnt(3)
	v_mfma_f32_16x16x32_bf16 v[26:29], v[30:33], v[86:89], v[26:29]
	ds_read_b128 v[30:33], v108 offset:50880
	s_waitcnt lgkmcnt(1)
	v_mfma_f32_16x16x32_bf16 v[26:29], v[42:45], v[82:85], v[26:29]
	ds_read_b128 v[42:45], v108 offset:50944
	v_mfma_f32_16x16x32_bf16 v[34:37], v[34:37], v[58:61], 0
	s_waitcnt lgkmcnt(1)
	v_mfma_f32_16x16x32_bf16 v[26:29], v[30:33], v[78:81], v[26:29]
	ds_read_b128 v[30:33], v108 offset:51008
	s_waitcnt lgkmcnt(1)
	v_mfma_f32_16x16x32_bf16 v[26:29], v[42:45], v[74:77], v[26:29]
	ds_read_b128 v[42:45], v108 offset:51072
	s_waitcnt lgkmcnt(1)
	v_mfma_f32_16x16x32_bf16 v[26:29], v[30:33], v[70:73], v[26:29]
	ds_read_b128 v[30:33], v108 offset:51136
	s_waitcnt lgkmcnt(1)
	v_mfma_f32_16x16x32_bf16 v[26:29], v[42:45], v[62:65], v[26:29]
	s_waitcnt lgkmcnt(0)
	v_mfma_f32_16x16x32_bf16 v[26:29], v[30:33], v[66:69], v[26:29]
	ds_read_b128 v[30:33], v108 offset:59264
	v_mfma_f32_16x16x32_bf16 v[34:37], v[38:41], v[86:89], v[34:37]
	ds_read_b128 v[38:41], v108 offset:59328
	s_waitcnt lgkmcnt(1)
	v_mfma_f32_16x16x32_bf16 v[30:33], v[30:33], v[82:85], v[34:37]
	s_nop 4
	ds_read_b128 v[34:37], v108 offset:59392
	s_waitcnt lgkmcnt(1)
	v_mfma_f32_16x16x32_bf16 v[30:33], v[38:41], v[78:81], v[30:33]
	ds_read_b128 v[38:41], v108 offset:59456
	s_waitcnt lgkmcnt(1)
	v_mfma_f32_16x16x32_bf16 v[30:33], v[34:37], v[74:77], v[30:33]
	ds_read_b128 v[34:37], v108 offset:59520
	s_waitcnt lgkmcnt(1)
	v_mfma_f32_16x16x32_bf16 v[30:33], v[38:41], v[70:73], v[30:33]
	ds_read_b128 v[38:41], v108 offset:59584
	s_waitcnt lgkmcnt(1)
	v_mfma_f32_16x16x32_bf16 v[30:33], v[34:37], v[62:65], v[30:33]
	s_waitcnt lgkmcnt(0)
	v_mfma_f32_16x16x32_bf16 v[30:33], v[38:41], v[66:69], v[30:33]
	ds_read_b128 v[34:37], v109
	ds_read_b128 v[38:41], v110
	ds_read_b128 v[42:45], v117
	ds_read_b128 v[46:49], v118
	ds_read_b128 v[50:53], v111
	s_waitcnt lgkmcnt(4)
	v_mfma_f32_16x16x32_bf16 v[34:37], v[34:37], v[58:61], 0
	s_waitcnt lgkmcnt(3)
	v_mfma_f32_16x16x32_bf16 v[34:37], v[38:41], v[86:89], v[34:37]
	ds_read_b128 v[38:41], v112
	s_waitcnt lgkmcnt(1)
	v_mfma_f32_16x16x32_bf16 v[34:37], v[50:53], v[82:85], v[34:37]
	ds_read_b128 v[50:53], v113
	v_mfma_f32_16x16x32_bf16 v[42:45], v[42:45], v[58:61], 0
	s_waitcnt lgkmcnt(1)
	v_mfma_f32_16x16x32_bf16 v[34:37], v[38:41], v[78:81], v[34:37]
	ds_read_b128 v[38:41], v114
	s_waitcnt lgkmcnt(1)
	v_mfma_f32_16x16x32_bf16 v[34:37], v[50:53], v[74:77], v[34:37]
	ds_read_b128 v[50:53], v115
	s_waitcnt lgkmcnt(1)
	v_mfma_f32_16x16x32_bf16 v[34:37], v[38:41], v[70:73], v[34:37]
	ds_read_b128 v[38:41], v116
	s_waitcnt lgkmcnt(1)
	v_mfma_f32_16x16x32_bf16 v[34:37], v[50:53], v[62:65], v[34:37]
	s_waitcnt lgkmcnt(0)
	v_mfma_f32_16x16x32_bf16 v[34:37], v[38:41], v[66:69], v[34:37]
	ds_read_b128 v[38:41], v119
	v_mfma_f32_16x16x32_bf16 v[42:45], v[46:49], v[86:89], v[42:45]
	ds_read_b128 v[46:49], v120
	s_waitcnt lgkmcnt(1)
	v_mfma_f32_16x16x32_bf16 v[38:41], v[38:41], v[82:85], v[42:45]
	s_nop 4
	ds_read_b128 v[42:45], v121
	s_waitcnt lgkmcnt(1)
	v_mfma_f32_16x16x32_bf16 v[38:41], v[46:49], v[78:81], v[38:41]
	ds_read_b128 v[46:49], v122
	s_waitcnt lgkmcnt(1)
	v_mfma_f32_16x16x32_bf16 v[38:41], v[42:45], v[74:77], v[38:41]
	ds_read_b128 v[42:45], v123
	s_waitcnt lgkmcnt(1)
	v_mfma_f32_16x16x32_bf16 v[38:41], v[46:49], v[70:73], v[38:41]
	ds_read_b128 v[46:49], v124
	s_waitcnt lgkmcnt(1)
	v_mfma_f32_16x16x32_bf16 v[38:41], v[42:45], v[62:65], v[38:41]
	s_waitcnt lgkmcnt(0)
	v_mfma_f32_16x16x32_bf16 v[38:41], v[46:49], v[66:69], v[38:41]
	ds_read_b128 v[42:45], v125
	ds_read_b128 v[46:49], v126
	ds_read_b128 v[50:53], v133
	ds_read_b128 v[54:57], v134
	ds_read_b128 v[200:203], v127
	s_waitcnt lgkmcnt(4)
	v_mfma_f32_16x16x32_bf16 v[42:45], v[42:45], v[58:61], 0
	s_waitcnt lgkmcnt(3)
	v_mfma_f32_16x16x32_bf16 v[42:45], v[46:49], v[86:89], v[42:45]
	ds_read_b128 v[46:49], v128
	s_waitcnt lgkmcnt(1)
	v_mfma_f32_16x16x32_bf16 v[42:45], v[200:203], v[82:85], v[42:45]
	ds_read_b128 v[200:203], v129
	v_mfma_f32_16x16x32_bf16 v[50:53], v[50:53], v[58:61], 0
	s_waitcnt lgkmcnt(1)
	v_mfma_f32_16x16x32_bf16 v[42:45], v[46:49], v[78:81], v[42:45]
	ds_read_b128 v[46:49], v130
	s_waitcnt lgkmcnt(1)
	v_mfma_f32_16x16x32_bf16 v[42:45], v[200:203], v[74:77], v[42:45]
	ds_read_b128 v[200:203], v131
	s_waitcnt lgkmcnt(1)
	v_mfma_f32_16x16x32_bf16 v[42:45], v[46:49], v[70:73], v[42:45]
	ds_read_b128 v[46:49], v132
	s_waitcnt lgkmcnt(1)
	v_mfma_f32_16x16x32_bf16 v[42:45], v[200:203], v[62:65], v[42:45]
	s_waitcnt lgkmcnt(0)
	v_mfma_f32_16x16x32_bf16 v[42:45], v[46:49], v[66:69], v[42:45]
	ds_read_b128 v[46:49], v135
	v_mfma_f32_16x16x32_bf16 v[50:53], v[54:57], v[86:89], v[50:53]
	ds_read_b128 v[54:57], v136
	s_waitcnt lgkmcnt(1)
	v_mfma_f32_16x16x32_bf16 v[46:49], v[46:49], v[82:85], v[50:53]
	s_nop 4
	ds_read_b128 v[50:53], v137
	s_waitcnt lgkmcnt(1)
	v_mfma_f32_16x16x32_bf16 v[46:49], v[54:57], v[78:81], v[46:49]
	ds_read_b128 v[54:57], v138
	s_waitcnt lgkmcnt(1)
	v_mfma_f32_16x16x32_bf16 v[46:49], v[50:53], v[74:77], v[46:49]
	ds_read_b128 v[50:53], v139
	s_waitcnt lgkmcnt(1)
	v_mfma_f32_16x16x32_bf16 v[46:49], v[54:57], v[70:73], v[46:49]
	ds_read_b128 v[54:57], v140
	s_waitcnt lgkmcnt(1)
	v_mfma_f32_16x16x32_bf16 v[46:49], v[50:53], v[62:65], v[46:49]
	s_waitcnt lgkmcnt(0)
	v_mfma_f32_16x16x32_bf16 v[46:49], v[54:57], v[66:69], v[46:49]
	ds_read_b128 v[50:53], v141
	ds_read_b128 v[54:57], v142
	ds_read_b128 v[200:203], v149
	ds_read_b128 v[204:207], v150
	ds_read_b128 v[208:211], v143
	s_waitcnt lgkmcnt(4)
	v_mfma_f32_16x16x32_bf16 v[50:53], v[50:53], v[58:61], 0
	s_waitcnt lgkmcnt(3)
	v_mfma_f32_16x16x32_bf16 v[50:53], v[54:57], v[86:89], v[50:53]
	ds_read_b128 v[54:57], v144
	s_waitcnt lgkmcnt(1)
	v_mfma_f32_16x16x32_bf16 v[50:53], v[208:211], v[82:85], v[50:53]
	ds_read_b128 v[208:211], v145
	v_mfma_f32_16x16x32_bf16 v[200:203], v[200:203], v[58:61], 0
	s_waitcnt lgkmcnt(1)
	v_mfma_f32_16x16x32_bf16 v[50:53], v[54:57], v[78:81], v[50:53]
	ds_read_b128 v[54:57], v146
	s_waitcnt lgkmcnt(1)
	v_mfma_f32_16x16x32_bf16 v[50:53], v[208:211], v[74:77], v[50:53]
	ds_read_b128 v[208:211], v147
	s_waitcnt lgkmcnt(1)
	v_mfma_f32_16x16x32_bf16 v[50:53], v[54:57], v[70:73], v[50:53]
	ds_read_b128 v[54:57], v148
	s_waitcnt lgkmcnt(1)
	v_mfma_f32_16x16x32_bf16 v[50:53], v[208:211], v[62:65], v[50:53]
	s_waitcnt lgkmcnt(0)
	v_mfma_f32_16x16x32_bf16 v[50:53], v[54:57], v[66:69], v[50:53]
	ds_read_b128 v[54:57], v151
	v_mfma_f32_16x16x32_bf16 v[200:203], v[204:207], v[86:89], v[200:203]
	ds_read_b128 v[204:207], v152
	s_waitcnt lgkmcnt(1)
	v_mfma_f32_16x16x32_bf16 v[54:57], v[54:57], v[82:85], v[200:203]
	s_nop 4
	ds_read_b128 v[200:203], v153
	s_waitcnt lgkmcnt(1)
	v_mfma_f32_16x16x32_bf16 v[54:57], v[204:207], v[78:81], v[54:57]
	ds_read_b128 v[204:207], v154
	s_waitcnt lgkmcnt(1)
	v_mfma_f32_16x16x32_bf16 v[54:57], v[200:203], v[74:77], v[54:57]
	ds_read_b128 v[200:203], v155
	s_waitcnt lgkmcnt(1)
	v_mfma_f32_16x16x32_bf16 v[54:57], v[204:207], v[70:73], v[54:57]
	ds_read_b128 v[204:207], v156
	s_waitcnt lgkmcnt(1)
	v_mfma_f32_16x16x32_bf16 v[54:57], v[200:203], v[62:65], v[54:57]
	s_waitcnt lgkmcnt(0)
	v_mfma_f32_16x16x32_bf16 v[54:57], v[204:207], v[66:69], v[54:57]
	ds_read_b128 v[200:203], v157
	ds_read_b128 v[204:207], v158
	ds_read_b128 v[208:211], v165
	ds_read_b128 v[212:215], v166
	s_waitcnt lgkmcnt(3)
	v_mfma_f32_16x16x32_bf16 v[200:203], v[200:203], v[58:61], 0
	s_waitcnt lgkmcnt(1)
	v_mfma_f32_16x16x32_bf16 v[208:211], v[208:211], v[58:61], 0
	ds_read_b128 v[58:61], v159
	v_mfma_f32_16x16x32_bf16 v[200:203], v[204:207], v[86:89], v[200:203]
	ds_read_b128 v[204:207], v160
	s_waitcnt lgkmcnt(1)
	v_mfma_f32_16x16x32_bf16 v[58:61], v[58:61], v[82:85], v[200:203]
	s_nop 4
	ds_read_b128 v[200:203], v161
	s_waitcnt lgkmcnt(1)
	v_mfma_f32_16x16x32_bf16 v[58:61], v[204:207], v[78:81], v[58:61]
	ds_read_b128 v[204:207], v162
	s_waitcnt lgkmcnt(1)
	v_mfma_f32_16x16x32_bf16 v[58:61], v[200:203], v[74:77], v[58:61]
	ds_read_b128 v[200:203], v163
	s_waitcnt lgkmcnt(1)
	v_mfma_f32_16x16x32_bf16 v[58:61], v[204:207], v[70:73], v[58:61]
	ds_read_b128 v[204:207], v164
	s_waitcnt lgkmcnt(1)
	v_mfma_f32_16x16x32_bf16 v[58:61], v[200:203], v[62:65], v[58:61]
	ds_read_b128 v[200:203], v167
	s_waitcnt lgkmcnt(1)
	v_mfma_f32_16x16x32_bf16 v[58:61], v[204:207], v[66:69], v[58:61]
	ds_read_b128 v[204:207], v168
	v_mfma_f32_16x16x32_bf16 v[86:89], v[212:215], v[86:89], v[208:211]
	s_waitcnt lgkmcnt(1)
	v_mfma_f32_16x16x32_bf16 v[82:85], v[200:203], v[82:85], v[86:89]
	s_waitcnt lgkmcnt(0)
	v_mfma_f32_16x16x32_bf16 v[78:81], v[204:207], v[78:81], v[82:85]
	s_nop 3
	ds_read_b128 v[86:89], v169
	s_nop 0
	ds_read_b128 v[82:85], v170
	s_waitcnt lgkmcnt(1)
	v_mfma_f32_16x16x32_bf16 v[74:77], v[86:89], v[74:77], v[78:81]
	s_nop 2
	ds_read_b128 v[78:81], v171
	s_waitcnt lgkmcnt(1)
	v_mfma_f32_16x16x32_bf16 v[70:73], v[82:85], v[70:73], v[74:77]
	s_nop 2
	ds_read_b128 v[74:77], v172
	s_waitcnt lgkmcnt(1)
	v_mfma_f32_16x16x32_bf16 v[62:65], v[78:81], v[62:65], v[70:73]
	s_waitcnt lgkmcnt(0)
	v_mfma_f32_16x16x32_bf16 v[62:65], v[74:77], v[66:69], v[62:65]
	s_barrier
	s_and_saveexec_b64 s[22:23], s[4:5]
	s_xor_b64 s[22:23], exec, s[22:23]
	s_cbranch_execz .LBB0_665
	s_lshl_b64 s[24:25], s[20:21], 1
	s_add_u32 s26, s0, s24
	s_addc_u32 s27, 0, s25
	v_lshl_add_u64 v[66:67], v[100:101], 0, s[26:27]
	s_mov_b64 s[26:27], 0
	v_mov_b32_e32 v68, v91
	v_mov_b32_e32 v69, v176
	v_mov_b32_e32 v90, v0

.LBB0_1443:
	v_lshl_add_u64 v[212:213], v[10:11], 0, v[2:3]
	global_load_dwordx4 v[38:41], v[212:213], off
	v_lshl_add_u64 v[212:213], v[4:5], 0, v[2:3]
	global_load_dwordx4 v[42:45], v[212:213], off
	v_lshl_add_u64 v[212:213], v[8:9], 0, v[2:3]
	global_load_dwordx4 v[46:49], v[212:213], off
	v_lshl_add_u64 v[212:213], v[6:7], 0, v[2:3]
	global_load_dwordx4 v[50:53], v[212:213], off
	v_lshl_add_u64 v[10:11], v[10:11], 0, s[12:13]
	v_lshl_add_u64 v[4:5], v[4:5], 0, s[12:13]
	v_lshl_add_u64 v[8:9], v[8:9], 0, s[12:13]
	v_lshl_add_u64 v[6:7], v[6:7], 0, s[12:13]
	v_lshl_add_u64 v[212:213], v[10:11], 0, v[2:3]
	global_load_dwordx4 v[54:57], v[212:213], off
	v_lshl_add_u64 v[212:213], v[4:5], 0, v[2:3]
	global_load_dwordx4 v[58:61], v[212:213], off
	v_lshl_add_u64 v[212:213], v[8:9], 0, v[2:3]
	global_load_dwordx4 v[62:65], v[212:213], off
	v_lshl_add_u64 v[212:213], v[6:7], 0, v[2:3]
	global_load_dwordx4 v[66:69], v[212:213], off
	v_lshl_add_u64 v[10:11], v[10:11], 0, s[12:13]
	v_lshl_add_u64 v[4:5], v[4:5], 0, s[12:13]
	v_lshl_add_u64 v[8:9], v[8:9], 0, s[12:13]
	v_lshl_add_u64 v[6:7], v[6:7], 0, s[12:13]
	v_lshl_add_u64 v[212:213], v[10:11], 0, v[2:3]
	global_load_dwordx4 v[70:73], v[212:213], off
	v_lshl_add_u64 v[212:213], v[4:5], 0, v[2:3]
	global_load_dwordx4 v[74:77], v[212:213], off
	v_lshl_add_u64 v[212:213], v[8:9], 0, v[2:3]
	global_load_dwordx4 v[78:81], v[212:213], off
	v_lshl_add_u64 v[212:213], v[6:7], 0, v[2:3]
	global_load_dwordx4 v[82:85], v[212:213], off
	v_lshl_add_u64 v[10:11], v[10:11], 0, s[12:13]
	v_lshl_add_u64 v[4:5], v[4:5], 0, s[12:13]
	v_lshl_add_u64 v[8:9], v[8:9], 0, s[12:13]
	v_lshl_add_u64 v[6:7], v[6:7], 0, s[12:13]
	v_lshl_add_u64 v[212:213], v[10:11], 0, v[2:3]
	global_load_dwordx4 v[86:89], v[212:213], off
	v_lshl_add_u64 v[212:213], v[4:5], 0, v[2:3]
	global_load_dwordx4 v[200:203], v[212:213], off
	v_lshl_add_u64 v[212:213], v[8:9], 0, v[2:3]
	global_load_dwordx4 v[204:207], v[212:213], off
	v_lshl_add_u64 v[212:213], v[6:7], 0, v[2:3]
	global_load_dwordx4 v[208:211], v[212:213], off
	v_add_u32_e32 v214, v15, v90
	s_waitcnt vmcnt(15)
	ds_write_b128 v214, v[38:41]
	v_add_u32_e32 v214, v16, v90
	s_waitcnt vmcnt(14)
	ds_write_b128 v214, v[42:45]
	v_add_u32_e32 v214, v14, v90
	s_waitcnt vmcnt(13)
	ds_write_b128 v214, v[46:49]
	v_add_u32_e32 v214, v13, v90
	s_waitcnt vmcnt(12)
	ds_write_b128 v214, v[50:53]
	v_add_u32_e32 v15, 0x8400, v15
	v_add_u32_e32 v16, 0x8400, v16
	v_add_u32_e32 v14, 0x8400, v14
	v_add_u32_e32 v13, 0x8400, v13
	v_add_u32_e32 v214, v15, v90
	s_waitcnt vmcnt(11)
	ds_write_b128 v214, v[54:57]
	v_add_u32_e32 v214, v16, v90
	s_waitcnt vmcnt(10)
	ds_write_b128 v214, v[58:61]
	v_add_u32_e32 v214, v14, v90
	s_waitcnt vmcnt(9)
	ds_write_b128 v214, v[62:65]
	v_add_u32_e32 v214, v13, v90
	s_waitcnt vmcnt(8)
	ds_write_b128 v214, v[66:69]
	v_add_u32_e32 v15, 0x8400, v15
	v_add_u32_e32 v16, 0x8400, v16
	v_add_u32_e32 v14, 0x8400, v14
	v_add_u32_e32 v13, 0x8400, v13
	v_add_u32_e32 v214, v15, v90
	s_waitcnt vmcnt(7)
	ds_write_b128 v214, v[70:73]
	v_add_u32_e32 v214, v16, v90
	s_waitcnt vmcnt(6)
	ds_write_b128 v214, v[74:77]
	v_add_u32_e32 v214, v14, v90
	s_waitcnt vmcnt(5)
	ds_write_b128 v214, v[78:81]
	v_add_u32_e32 v214, v13, v90
	s_waitcnt vmcnt(4)
	ds_write_b128 v214, v[82:85]
	v_add_u32_e32 v15, 0x8400, v15
	v_add_u32_e32 v16, 0x8400, v16
	v_add_u32_e32 v14, 0x8400, v14
	v_add_u32_e32 v13, 0x8400, v13
	v_add_u32_e32 v214, v15, v90
	s_waitcnt vmcnt(3)
	ds_write_b128 v214, v[86:89]
	v_add_u32_e32 v214, v16, v90
	s_waitcnt vmcnt(2)
	ds_write_b128 v214, v[200:203]
	v_add_u32_e32 v214, v14, v90
	s_waitcnt vmcnt(1)
	ds_write_b128 v214, v[204:207]
	v_add_u32_e32 v214, v13, v90
	s_waitcnt vmcnt(0)
	ds_write_b128 v214, v[208:211]
	s_or_b64 exec, exec, s[20:21]
	s_lshl_b32 s20, s42, 7
	s_and_b32 s20, s20, 0xf80
	s_and_b32 s45, s23, 3
	s_add_i32 s44, s20, s28
	s_lshl_b32 s20, s22, 8
	s_lshl_b32 s43, s22, 12
	s_lshl_b32 s0, s0, 18
	s_ashr_i32 s21, s20, 31
	s_add_i32 s44, s44, s43
	s_lshl_b32 s46, s45, 9
	s_add_u32 s22, s29, s46
	s_addc_u32 s23, s30, 0
	v_or_b32_e32 v190, s44, v106
	v_mov_b64_e32 v[2:3], s[22:23]
	v_mad_i64_i32 v[2:3], s[22:23], v190, s39, v[2:3]
	v_mov_b32_e32 v103, v91
	v_lshl_add_u64 v[2:3], v[2:3], 0, v[102:103]
	global_load_dwordx4 v[58:61], v[2:3], off
	global_load_dwordx4 v[86:89], v[2:3], off offset:64
	global_load_dwordx4 v[82:85], v[2:3], off offset:128
	global_load_dwordx4 v[78:81], v[2:3], off offset:192
	global_load_dwordx4 v[74:77], v[2:3], off offset:256
	global_load_dwordx4 v[70:73], v[2:3], off offset:320
	global_load_dwordx4 v[62:65], v[2:3], off offset:384
	global_load_dwordx4 v[66:69], v[2:3], off offset:448
	s_waitcnt lgkmcnt(0)
	s_barrier
	ds_read_b128 v[2:5], v108
	ds_read_b128 v[6:9], v108 offset:64
	ds_read_b128 v[10:13], v108 offset:8448
	ds_read_b128 v[14:17], v108 offset:8512
	s_waitcnt vmcnt(7) lgkmcnt(3)
	v_mfma_f32_16x16x32_bf16 v[2:5], v[2:5], v[58:61], 0
	s_waitcnt lgkmcnt(1)
	v_mfma_f32_16x16x32_bf16 v[10:13], v[10:13], v[58:61], 0
	s_waitcnt vmcnt(6)
	v_mfma_f32_16x16x32_bf16 v[2:5], v[6:9], v[86:89], v[2:5]
	s_waitcnt lgkmcnt(0)
	v_mfma_f32_16x16x32_bf16 v[6:9], v[14:17], v[86:89], v[10:13]
	s_nop 3
	ds_read_b128 v[10:13], v108 offset:128
	ds_read_b128 v[14:17], v108 offset:192
	s_waitcnt vmcnt(5) lgkmcnt(1)
	v_mfma_f32_16x16x32_bf16 v[2:5], v[10:13], v[82:85], v[2:5]
	ds_read_b128 v[10:13], v108 offset:8576
	ds_read_b128 v[18:21], v108 offset:8640
	s_waitcnt lgkmcnt(1)
	v_mfma_f32_16x16x32_bf16 v[6:9], v[10:13], v[82:85], v[6:9]
	s_waitcnt vmcnt(4)
	v_mfma_f32_16x16x32_bf16 v[2:5], v[14:17], v[78:81], v[2:5]
	ds_read_b128 v[10:13], v108 offset:256
	ds_read_b128 v[14:17], v108 offset:320
	s_waitcnt lgkmcnt(2)
	v_mfma_f32_16x16x32_bf16 v[6:9], v[18:21], v[78:81], v[6:9]
	s_waitcnt vmcnt(3) lgkmcnt(1)
	v_mfma_f32_16x16x32_bf16 v[2:5], v[10:13], v[74:77], v[2:5]
	ds_read_b128 v[10:13], v108 offset:8704
	ds_read_b128 v[18:21], v108 offset:8768
	s_waitcnt lgkmcnt(1)
	v_mfma_f32_16x16x32_bf16 v[6:9], v[10:13], v[74:77], v[6:9]
	s_waitcnt vmcnt(2)
	v_mfma_f32_16x16x32_bf16 v[2:5], v[14:17], v[70:73], v[2:5]
	ds_read_b128 v[10:13], v108 offset:384
	ds_read_b128 v[14:17], v108 offset:448
	s_waitcnt lgkmcnt(2)
	v_mfma_f32_16x16x32_bf16 v[6:9], v[18:21], v[70:73], v[6:9]
	s_waitcnt vmcnt(1) lgkmcnt(1)
	v_mfma_f32_16x16x32_bf16 v[2:5], v[10:13], v[62:65], v[2:5]
	ds_read_b128 v[10:13], v108 offset:8832
	ds_read_b128 v[18:21], v108 offset:8896
	s_waitcnt lgkmcnt(1)
	v_mfma_f32_16x16x32_bf16 v[10:13], v[10:13], v[62:65], v[6:9]
	s_waitcnt vmcnt(0)
	v_mfma_f32_16x16x32_bf16 v[6:9], v[14:17], v[66:69], v[2:5]
	s_waitcnt lgkmcnt(0)
	v_mfma_f32_16x16x32_bf16 v[2:5], v[18:21], v[66:69], v[10:13]
	s_nop 3
	ds_read_b128 v[10:13], v108 offset:16896
	ds_read_b128 v[14:17], v108 offset:16960
	ds_read_b128 v[18:21], v108 offset:25344
	ds_read_b128 v[22:25], v108 offset:25408
	ds_read_b128 v[26:29], v108 offset:17024
	s_waitcnt lgkmcnt(4)
	v_mfma_f32_16x16x32_bf16 v[10:13], v[10:13], v[58:61], 0
	s_waitcnt lgkmcnt(3)
	v_mfma_f32_16x16x32_bf16 v[10:13], v[14:17], v[86:89], v[10:13]
	ds_read_b128 v[14:17], v108 offset:17088
	s_waitcnt lgkmcnt(1)
	v_mfma_f32_16x16x32_bf16 v[10:13], v[26:29], v[82:85], v[10:13]
	ds_read_b128 v[26:29], v108 offset:17152
	v_mfma_f32_16x16x32_bf16 v[18:21], v[18:21], v[58:61], 0
	s_waitcnt lgkmcnt(1)
	v_mfma_f32_16x16x32_bf16 v[10:13], v[14:17], v[78:81], v[10:13]
	ds_read_b128 v[14:17], v108 offset:17216
	s_waitcnt lgkmcnt(1)
	v_mfma_f32_16x16x32_bf16 v[10:13], v[26:29], v[74:77], v[10:13]
	ds_read_b128 v[26:29], v108 offset:17280
	s_waitcnt lgkmcnt(1)
	v_mfma_f32_16x16x32_bf16 v[10:13], v[14:17], v[70:73], v[10:13]
	ds_read_b128 v[14:17], v108 offset:17344
	s_waitcnt lgkmcnt(1)
	v_mfma_f32_16x16x32_bf16 v[10:13], v[26:29], v[62:65], v[10:13]
	s_waitcnt lgkmcnt(0)
	v_mfma_f32_16x16x32_bf16 v[10:13], v[14:17], v[66:69], v[10:13]
	ds_read_b128 v[14:17], v108 offset:25472
	v_mfma_f32_16x16x32_bf16 v[18:21], v[22:25], v[86:89], v[18:21]
	ds_read_b128 v[22:25], v108 offset:25536
	s_waitcnt lgkmcnt(1)
	v_mfma_f32_16x16x32_bf16 v[14:17], v[14:17], v[82:85], v[18:21]
	s_nop 4
	ds_read_b128 v[18:21], v108 offset:25600
	s_waitcnt lgkmcnt(1)
	v_mfma_f32_16x16x32_bf16 v[14:17], v[22:25], v[78:81], v[14:17]
	ds_read_b128 v[22:25], v108 offset:25664
	s_waitcnt lgkmcnt(1)
	v_mfma_f32_16x16x32_bf16 v[14:17], v[18:21], v[74:77], v[14:17]
	ds_read_b128 v[18:21], v108 offset:25728
	s_waitcnt lgkmcnt(1)
	v_mfma_f32_16x16x32_bf16 v[14:17], v[22:25], v[70:73], v[14:17]
	ds_read_b128 v[22:25], v108 offset:25792
	s_waitcnt lgkmcnt(1)
	v_mfma_f32_16x16x32_bf16 v[14:17], v[18:21], v[62:65], v[14:17]
	s_waitcnt lgkmcnt(0)
	v_mfma_f32_16x16x32_bf16 v[14:17], v[22:25], v[66:69], v[14:17]
	ds_read_b128 v[18:21], v108 offset:33792
	ds_read_b128 v[22:25], v108 offset:33856
	ds_read_b128 v[26:29], v108 offset:42240
	ds_read_b128 v[30:33], v108 offset:42304
	ds_read_b128 v[34:37], v108 offset:33920
	s_waitcnt lgkmcnt(4)
	v_mfma_f32_16x16x32_bf16 v[18:21], v[18:21], v[58:61], 0
	s_waitcnt lgkmcnt(3)
	v_mfma_f32_16x16x32_bf16 v[18:21], v[22:25], v[86:89], v[18:21]
	ds_read_b128 v[22:25], v108 offset:33984
	s_waitcnt lgkmcnt(1)
	v_mfma_f32_16x16x32_bf16 v[18:21], v[34:37], v[82:85], v[18:21]
	ds_read_b128 v[34:37], v108 offset:34048
	v_mfma_f32_16x16x32_bf16 v[26:29], v[26:29], v[58:61], 0
	s_waitcnt lgkmcnt(1)
	v_mfma_f32_16x16x32_bf16 v[18:21], v[22:25], v[78:81], v[18:21]
	ds_read_b128 v[22:25], v108 offset:34112
	s_waitcnt lgkmcnt(1)
	v_mfma_f32_16x16x32_bf16 v[18:21], v[34:37], v[74:77], v[18:21]
	ds_read_b128 v[34:37], v108 offset:34176
	s_waitcnt lgkmcnt(1)
	v_mfma_f32_16x16x32_bf16 v[18:21], v[22:25], v[70:73], v[18:21]
	ds_read_b128 v[22:25], v108 offset:34240
	s_waitcnt lgkmcnt(1)
	v_mfma_f32_16x16x32_bf16 v[18:21], v[34:37], v[62:65], v[18:21]
	s_waitcnt lgkmcnt(0)
	v_mfma_f32_16x16x32_bf16 v[18:21], v[22:25], v[66:69], v[18:21]
	ds_read_b128 v[22:25], v108 offset:42368
	v_mfma_f32_16x16x32_bf16 v[26:29], v[30:33], v[86:89], v[26:29]
	ds_read_b128 v[30:33], v108 offset:42432
	s_waitcnt lgkmcnt(1)
	v_mfma_f32_16x16x32_bf16 v[22:25], v[22:25], v[82:85], v[26:29]
	s_nop 4
	ds_read_b128 v[26:29], v108 offset:42496
	s_waitcnt lgkmcnt(1)
	v_mfma_f32_16x16x32_bf16 v[22:25], v[30:33], v[78:81], v[22:25]
	ds_read_b128 v[30:33], v108 offset:42560
	s_waitcnt lgkmcnt(1)
	v_mfma_f32_16x16x32_bf16 v[22:25], v[26:29], v[74:77], v[22:25]
	ds_read_b128 v[26:29], v108 offset:42624
	s_waitcnt lgkmcnt(1)
	v_mfma_f32_16x16x32_bf16 v[22:25], v[30:33], v[70:73], v[22:25]
	ds_read_b128 v[30:33], v108 offset:42688
	s_waitcnt lgkmcnt(1)
	v_mfma_f32_16x16x32_bf16 v[22:25], v[26:29], v[62:65], v[22:25]
	s_waitcnt lgkmcnt(0)
	v_mfma_f32_16x16x32_bf16 v[22:25], v[30:33], v[66:69], v[22:25]
	ds_read_b128 v[26:29], v108 offset:50688
	ds_read_b128 v[30:33], v108 offset:50752
	ds_read_b128 v[34:37], v108 offset:59136
	ds_read_b128 v[38:41], v108 offset:59200
	ds_read_b128 v[42:45], v108 offset:50816
	s_waitcnt lgkmcnt(4)
	v_mfma_f32_16x16x32_bf16 v[26:29], v[26:29], v[58:61], 0
	s_waitcnt lgkmcnt(3)
	v_mfma_f32_16x16x32_bf16 v[26:29], v[30:33], v[86:89], v[26:29]
	ds_read_b128 v[30:33], v108 offset:50880
	s_waitcnt lgkmcnt(1)
	v_mfma_f32_16x16x32_bf16 v[26:29], v[42:45], v[82:85], v[26:29]
	ds_read_b128 v[42:45], v108 offset:50944
	v_mfma_f32_16x16x32_bf16 v[34:37], v[34:37], v[58:61], 0
	s_waitcnt lgkmcnt(1)
	v_mfma_f32_16x16x32_bf16 v[26:29], v[30:33], v[78:81], v[26:29]
	ds_read_b128 v[30:33], v108 offset:51008
	s_waitcnt lgkmcnt(1)
	v_mfma_f32_16x16x32_bf16 v[26:29], v[42:45], v[74:77], v[26:29]
	ds_read_b128 v[42:45], v108 offset:51072
	s_waitcnt lgkmcnt(1)
	v_mfma_f32_16x16x32_bf16 v[26:29], v[30:33], v[70:73], v[26:29]
	ds_read_b128 v[30:33], v108 offset:51136
	s_waitcnt lgkmcnt(1)
	v_mfma_f32_16x16x32_bf16 v[26:29], v[42:45], v[62:65], v[26:29]
	s_waitcnt lgkmcnt(0)
	v_mfma_f32_16x16x32_bf16 v[26:29], v[30:33], v[66:69], v[26:29]
	ds_read_b128 v[30:33], v108 offset:59264
	v_mfma_f32_16x16x32_bf16 v[34:37], v[38:41], v[86:89], v[34:37]
	ds_read_b128 v[38:41], v108 offset:59328
	s_waitcnt lgkmcnt(1)
	v_mfma_f32_16x16x32_bf16 v[30:33], v[30:33], v[82:85], v[34:37]
	s_nop 4
	ds_read_b128 v[34:37], v108 offset:59392
	s_waitcnt lgkmcnt(1)
	v_mfma_f32_16x16x32_bf16 v[30:33], v[38:41], v[78:81], v[30:33]
	ds_read_b128 v[38:41], v108 offset:59456
	s_waitcnt lgkmcnt(1)
	v_mfma_f32_16x16x32_bf16 v[30:33], v[34:37], v[74:77], v[30:33]
	ds_read_b128 v[34:37], v108 offset:59520
	s_waitcnt lgkmcnt(1)
	v_mfma_f32_16x16x32_bf16 v[30:33], v[38:41], v[70:73], v[30:33]
	ds_read_b128 v[38:41], v108 offset:59584
	s_waitcnt lgkmcnt(1)
	v_mfma_f32_16x16x32_bf16 v[30:33], v[34:37], v[62:65], v[30:33]
	s_waitcnt lgkmcnt(0)
	v_mfma_f32_16x16x32_bf16 v[30:33], v[38:41], v[66:69], v[30:33]
	ds_read_b128 v[34:37], v109
	ds_read_b128 v[38:41], v110
	ds_read_b128 v[42:45], v117
	ds_read_b128 v[46:49], v118
	ds_read_b128 v[50:53], v111
	s_waitcnt lgkmcnt(4)
	v_mfma_f32_16x16x32_bf16 v[34:37], v[34:37], v[58:61], 0
	s_waitcnt lgkmcnt(3)
	v_mfma_f32_16x16x32_bf16 v[34:37], v[38:41], v[86:89], v[34:37]
	ds_read_b128 v[38:41], v112
	s_waitcnt lgkmcnt(1)
	v_mfma_f32_16x16x32_bf16 v[34:37], v[50:53], v[82:85], v[34:37]
	ds_read_b128 v[50:53], v113
	v_mfma_f32_16x16x32_bf16 v[42:45], v[42:45], v[58:61], 0
	s_waitcnt lgkmcnt(1)
	v_mfma_f32_16x16x32_bf16 v[34:37], v[38:41], v[78:81], v[34:37]
	ds_read_b128 v[38:41], v114
	s_waitcnt lgkmcnt(1)
	v_mfma_f32_16x16x32_bf16 v[34:37], v[50:53], v[74:77], v[34:37]
	ds_read_b128 v[50:53], v115
	s_waitcnt lgkmcnt(1)
	v_mfma_f32_16x16x32_bf16 v[34:37], v[38:41], v[70:73], v[34:37]
	ds_read_b128 v[38:41], v116
	s_waitcnt lgkmcnt(1)
	v_mfma_f32_16x16x32_bf16 v[34:37], v[50:53], v[62:65], v[34:37]
	s_waitcnt lgkmcnt(0)
	v_mfma_f32_16x16x32_bf16 v[34:37], v[38:41], v[66:69], v[34:37]
	ds_read_b128 v[38:41], v119
	v_mfma_f32_16x16x32_bf16 v[42:45], v[46:49], v[86:89], v[42:45]
	ds_read_b128 v[46:49], v120
	s_waitcnt lgkmcnt(1)
	v_mfma_f32_16x16x32_bf16 v[38:41], v[38:41], v[82:85], v[42:45]
	s_nop 4
	ds_read_b128 v[42:45], v121
	s_waitcnt lgkmcnt(1)
	v_mfma_f32_16x16x32_bf16 v[38:41], v[46:49], v[78:81], v[38:41]
	ds_read_b128 v[46:49], v122
	s_waitcnt lgkmcnt(1)
	v_mfma_f32_16x16x32_bf16 v[38:41], v[42:45], v[74:77], v[38:41]
	ds_read_b128 v[42:45], v123
	s_waitcnt lgkmcnt(1)
	v_mfma_f32_16x16x32_bf16 v[38:41], v[46:49], v[70:73], v[38:41]
	ds_read_b128 v[46:49], v124
	s_waitcnt lgkmcnt(1)
	v_mfma_f32_16x16x32_bf16 v[38:41], v[42:45], v[62:65], v[38:41]
	s_waitcnt lgkmcnt(0)
	v_mfma_f32_16x16x32_bf16 v[38:41], v[46:49], v[66:69], v[38:41]
	ds_read_b128 v[42:45], v125
	ds_read_b128 v[46:49], v126
	ds_read_b128 v[50:53], v133
	ds_read_b128 v[54:57], v134
	ds_read_b128 v[192:195], v127
	s_waitcnt lgkmcnt(4)
	v_mfma_f32_16x16x32_bf16 v[42:45], v[42:45], v[58:61], 0
	s_waitcnt lgkmcnt(3)
	v_mfma_f32_16x16x32_bf16 v[42:45], v[46:49], v[86:89], v[42:45]
	ds_read_b128 v[46:49], v128
	s_waitcnt lgkmcnt(1)
	v_mfma_f32_16x16x32_bf16 v[42:45], v[192:195], v[82:85], v[42:45]
	ds_read_b128 v[192:195], v129
	v_mfma_f32_16x16x32_bf16 v[50:53], v[50:53], v[58:61], 0
	s_waitcnt lgkmcnt(1)
	v_mfma_f32_16x16x32_bf16 v[42:45], v[46:49], v[78:81], v[42:45]
	ds_read_b128 v[46:49], v130
	s_waitcnt lgkmcnt(1)
	v_mfma_f32_16x16x32_bf16 v[42:45], v[192:195], v[74:77], v[42:45]
	ds_read_b128 v[192:195], v131
	s_waitcnt lgkmcnt(1)
	v_mfma_f32_16x16x32_bf16 v[42:45], v[46:49], v[70:73], v[42:45]
	ds_read_b128 v[46:49], v132
	s_waitcnt lgkmcnt(1)
	v_mfma_f32_16x16x32_bf16 v[42:45], v[192:195], v[62:65], v[42:45]
	s_waitcnt lgkmcnt(0)
	v_mfma_f32_16x16x32_bf16 v[42:45], v[46:49], v[66:69], v[42:45]
	ds_read_b128 v[46:49], v135
	v_mfma_f32_16x16x32_bf16 v[50:53], v[54:57], v[86:89], v[50:53]
	ds_read_b128 v[54:57], v136
	s_waitcnt lgkmcnt(1)
	v_mfma_f32_16x16x32_bf16 v[46:49], v[46:49], v[82:85], v[50:53]
	s_nop 4
	ds_read_b128 v[50:53], v137
	s_waitcnt lgkmcnt(1)
	v_mfma_f32_16x16x32_bf16 v[46:49], v[54:57], v[78:81], v[46:49]
	ds_read_b128 v[54:57], v138
	s_waitcnt lgkmcnt(1)
	v_mfma_f32_16x16x32_bf16 v[46:49], v[50:53], v[74:77], v[46:49]
	ds_read_b128 v[50:53], v139
	s_waitcnt lgkmcnt(1)
	v_mfma_f32_16x16x32_bf16 v[46:49], v[54:57], v[70:73], v[46:49]
	ds_read_b128 v[54:57], v140
	s_waitcnt lgkmcnt(1)
	v_mfma_f32_16x16x32_bf16 v[46:49], v[50:53], v[62:65], v[46:49]
	s_waitcnt lgkmcnt(0)
	v_mfma_f32_16x16x32_bf16 v[46:49], v[54:57], v[66:69], v[46:49]
	ds_read_b128 v[50:53], v141
	ds_read_b128 v[54:57], v142
	ds_read_b128 v[192:195], v149
	ds_read_b128 v[196:199], v150
	ds_read_b128 v[200:203], v143
	s_waitcnt lgkmcnt(4)
	v_mfma_f32_16x16x32_bf16 v[50:53], v[50:53], v[58:61], 0
	s_waitcnt lgkmcnt(3)
	v_mfma_f32_16x16x32_bf16 v[50:53], v[54:57], v[86:89], v[50:53]
	ds_read_b128 v[54:57], v144
	s_waitcnt lgkmcnt(1)
	v_mfma_f32_16x16x32_bf16 v[50:53], v[200:203], v[82:85], v[50:53]
	ds_read_b128 v[200:203], v145
	v_mfma_f32_16x16x32_bf16 v[192:195], v[192:195], v[58:61], 0
	s_waitcnt lgkmcnt(1)
	v_mfma_f32_16x16x32_bf16 v[50:53], v[54:57], v[78:81], v[50:53]
	ds_read_b128 v[54:57], v146
	s_waitcnt lgkmcnt(1)
	v_mfma_f32_16x16x32_bf16 v[50:53], v[200:203], v[74:77], v[50:53]
	ds_read_b128 v[200:203], v147
	s_waitcnt lgkmcnt(1)
	v_mfma_f32_16x16x32_bf16 v[50:53], v[54:57], v[70:73], v[50:53]
	ds_read_b128 v[54:57], v148
	s_waitcnt lgkmcnt(1)
	v_mfma_f32_16x16x32_bf16 v[50:53], v[200:203], v[62:65], v[50:53]
	s_waitcnt lgkmcnt(0)
	v_mfma_f32_16x16x32_bf16 v[50:53], v[54:57], v[66:69], v[50:53]
	ds_read_b128 v[54:57], v151
	v_mfma_f32_16x16x32_bf16 v[192:195], v[196:199], v[86:89], v[192:195]
	ds_read_b128 v[196:199], v152
	s_waitcnt lgkmcnt(1)
	v_mfma_f32_16x16x32_bf16 v[54:57], v[54:57], v[82:85], v[192:195]
	s_nop 4
	ds_read_b128 v[192:195], v153
	s_waitcnt lgkmcnt(1)
	v_mfma_f32_16x16x32_bf16 v[54:57], v[196:199], v[78:81], v[54:57]
	ds_read_b128 v[196:199], v154
	s_waitcnt lgkmcnt(1)
	v_mfma_f32_16x16x32_bf16 v[54:57], v[192:195], v[74:77], v[54:57]
	ds_read_b128 v[192:195], v155
	s_waitcnt lgkmcnt(1)
	v_mfma_f32_16x16x32_bf16 v[54:57], v[196:199], v[70:73], v[54:57]
	ds_read_b128 v[196:199], v156
	s_waitcnt lgkmcnt(1)
	v_mfma_f32_16x16x32_bf16 v[54:57], v[192:195], v[62:65], v[54:57]
	s_waitcnt lgkmcnt(0)
	v_mfma_f32_16x16x32_bf16 v[54:57], v[196:199], v[66:69], v[54:57]
	ds_read_b128 v[192:195], v157
	ds_read_b128 v[196:199], v158
	ds_read_b128 v[200:203], v165
	ds_read_b128 v[204:207], v166
	s_waitcnt lgkmcnt(3)
	v_mfma_f32_16x16x32_bf16 v[192:195], v[192:195], v[58:61], 0
	s_waitcnt lgkmcnt(1)
	v_mfma_f32_16x16x32_bf16 v[200:203], v[200:203], v[58:61], 0
	ds_read_b128 v[58:61], v159
	v_mfma_f32_16x16x32_bf16 v[192:195], v[196:199], v[86:89], v[192:195]
	ds_read_b128 v[196:199], v160
	s_waitcnt lgkmcnt(1)
	v_mfma_f32_16x16x32_bf16 v[58:61], v[58:61], v[82:85], v[192:195]
	s_nop 4
	ds_read_b128 v[192:195], v161
	s_waitcnt lgkmcnt(1)
	v_mfma_f32_16x16x32_bf16 v[58:61], v[196:199], v[78:81], v[58:61]
	ds_read_b128 v[196:199], v162
	s_waitcnt lgkmcnt(1)
	v_mfma_f32_16x16x32_bf16 v[58:61], v[192:195], v[74:77], v[58:61]
	ds_read_b128 v[192:195], v163
	s_waitcnt lgkmcnt(1)
	v_mfma_f32_16x16x32_bf16 v[58:61], v[196:199], v[70:73], v[58:61]
	ds_read_b128 v[196:199], v164
	s_waitcnt lgkmcnt(1)
	v_mfma_f32_16x16x32_bf16 v[58:61], v[192:195], v[62:65], v[58:61]
	ds_read_b128 v[192:195], v167
	s_waitcnt lgkmcnt(1)
	v_mfma_f32_16x16x32_bf16 v[58:61], v[196:199], v[66:69], v[58:61]
	ds_read_b128 v[196:199], v168
	v_mfma_f32_16x16x32_bf16 v[86:89], v[204:207], v[86:89], v[200:203]
	s_waitcnt lgkmcnt(1)
	v_mfma_f32_16x16x32_bf16 v[82:85], v[192:195], v[82:85], v[86:89]
	s_waitcnt lgkmcnt(0)
	v_mfma_f32_16x16x32_bf16 v[78:81], v[196:199], v[78:81], v[82:85]
	s_nop 3
	ds_read_b128 v[86:89], v169
	s_nop 0
	ds_read_b128 v[82:85], v170
	s_waitcnt lgkmcnt(1)
	v_mfma_f32_16x16x32_bf16 v[74:77], v[86:89], v[74:77], v[78:81]
	s_nop 2
	ds_read_b128 v[78:81], v171
	s_waitcnt lgkmcnt(1)
	v_mfma_f32_16x16x32_bf16 v[70:73], v[82:85], v[70:73], v[74:77]
	s_nop 2
	ds_read_b128 v[74:77], v172
	s_waitcnt lgkmcnt(1)
	v_mfma_f32_16x16x32_bf16 v[62:65], v[78:81], v[62:65], v[70:73]
	s_waitcnt lgkmcnt(0)
	v_mfma_f32_16x16x32_bf16 v[62:65], v[74:77], v[66:69], v[62:65]
	s_barrier
	s_and_saveexec_b64 s[24:25], s[4:5]
	s_xor_b64 s[24:25], exec, s[24:25]
	s_cbranch_execz .LBB0_1448
	s_lshl_b64 s[22:23], s[20:21], 1
	s_add_u32 s26, s0, s22
	s_addc_u32 s27, 0, s23
	v_lshl_add_u64 v[66:67], v[100:101], 0, s[26:27]
	s_mov_b64 s[26:27], 0
	v_mov_b32_e32 v68, v91
	v_mov_b32_e32 v69, v176
	v_mov_b32_e32 v90, v0
